# adds: wave-uniform chunk mask test in attention tail tiles; P8 residual epilogue base-row loads issued 8 at a time
# speedup vs baseline: 1.0020x; 1.0020x over previous
; __device__ __forceinline__ void cmask(f32x16&p0,f32x16&p1,int jb,int qrel,int hi,lds_cfptr bt){
;     ...
;   const int kb=64*jb+4*hi; const int qlim=(qrel|63)-kb; const int base=kb-qrel+128;
;   #pragma unroll
;   for(int r=0;r<16;++r){const int ko=(r&3)+8*(r>>2);
;     const float b0=bt[med3i(base+ko,0,192)], b1=bt[med3i(base+ko+32,0,192)];
;     p0[r]=(ko>qlim)?NEG:p0[r]+b0; p1[r]=(ko+32>qlim)?NEG:p1[r]+b1;
;     if((r%CM_GRP)==CM_GRP-1)__builtin_amdgcn_sched_barrier(0); }
.LBB0_403:
	v_add_u32_e32 v116, s94, v216
	ds_read_b128 v[184:187], v116
	ds_read_b128 v[188:191], v116 offset:512
	ds_read_b128 v[180:183], v116 offset:2048
	ds_read_b128 v[176:179], v116 offset:2560
	ds_read_b128 v[172:175], v116 offset:4096
	ds_read_b128 v[168:171], v116 offset:4608
	ds_read_b128 v[164:167], v116 offset:6144
	ds_read_b128 v[160:163], v116 offset:6656
	s_add_i32 s95, s91, s92
	s_add_i32 s34, s95, 2
	s_lshl_b32 s34, s34, 6
	s_addk_i32 s34, 0x9a
	s_sub_i32 s34, s34, s57
	s_cmp_le_i32 s34, 0
	s_cbranch_scc1 .LBB0_405
	v_add_u32_e32 v232, 64, v218
	v_cmp_lt_i32_e32 vcc, -1, v232
	s_cbranch_vccz .Lcm_masked_A
	v_add_u32_e32 v116, 0xffffffa5, v217
	v_med3_i32 v117, v116, 0, v212
	v_max_i32_e32 v116, 0xffffffe0, v116
	v_add_u32_e32 v116, 32, v116
	v_min_u32_e32 v116, 0xc0, v116
	v_lshl_add_u32 v118, v116, 2, s15
	v_add_u32_e32 v116, 0xffffffa6, v217
	v_med3_i32 v119, v116, 0, v212
	v_max_i32_e32 v116, 0xffffffe0, v116
	v_add_u32_e32 v116, 32, v116
	v_min_u32_e32 v116, 0xc0, v116
	v_lshl_add_u32 v120, v116, 2, s15
	v_add_u32_e32 v116, 0xffffffa7, v217
	v_med3_i32 v121, v116, 0, v212
	v_max_i32_e32 v116, 0xffffffe0, v116
	v_add_u32_e32 v116, 32, v116
	v_min_u32_e32 v116, 0xc0, v116
	v_lshl_add_u32 v122, v116, 2, s15
	v_add_u32_e32 v116, 0xffffffa8, v217
	v_med3_i32 v123, v116, 0, v212
	v_max_i32_e32 v116, 0xffffffe0, v116
	v_add_u32_e32 v116, 32, v116
	v_min_u32_e32 v116, 0xc0, v116
	v_lshl_add_u32 v117, v117, 2, s15
	v_lshl_add_u32 v119, v119, 2, s15
	v_lshl_add_u32 v121, v121, 2, s15
	v_lshl_add_u32 v123, v123, 2, s15
	v_lshl_add_u32 v124, v116, 2, s15
	ds_read_b32 v116, v117
	ds_read_b32 v118, v118
	ds_read_b32 v117, v119
	ds_read_b32 v119, v120
	ds_read_b32 v120, v121
	ds_read_b32 v122, v122
	ds_read_b32 v121, v123
	ds_read_b32 v123, v124
	v_add_u32_e32 v124, 0xffffffad, v217
	v_med3_i32 v125, v124, 0, v212
	v_max_i32_e32 v124, 0xffffffe0, v124
	v_add_u32_e32 v124, 32, v124
	v_min_u32_e32 v124, 0xc0, v124
	v_lshl_add_u32 v126, v124, 2, s15
	v_add_u32_e32 v124, 0xffffffae, v217
	v_med3_i32 v127, v124, 0, v212
	v_max_i32_e32 v124, 0xffffffe0, v124
	v_add_u32_e32 v124, 32, v124
	v_min_u32_e32 v124, 0xc0, v124
	v_lshl_add_u32 v136, v124, 2, s15
	v_add_u32_e32 v124, 0xffffffaf, v217
	v_med3_i32 v137, v124, 0, v212
	v_max_i32_e32 v124, 0xffffffe0, v124
	v_add_u32_e32 v124, 32, v124
	v_min_u32_e32 v124, 0xc0, v124
	v_lshl_add_u32 v138, v124, 2, s15
	v_add_u32_e32 v124, 0xffffffb0, v217
	v_med3_i32 v139, v124, 0, v212
	v_max_i32_e32 v124, 0xffffffe0, v124
	v_add_u32_e32 v124, 32, v124
	v_min_u32_e32 v124, 0xc0, v124
	v_lshl_add_u32 v125, v125, 2, s15
	v_lshl_add_u32 v127, v127, 2, s15
	v_lshl_add_u32 v137, v137, 2, s15
	v_lshl_add_u32 v139, v139, 2, s15
	v_lshl_add_u32 v140, v124, 2, s15
	ds_read_b32 v124, v125
	ds_read_b32 v126, v126
	ds_read_b32 v125, v127
	ds_read_b32 v127, v136
	ds_read_b32 v136, v137
	ds_read_b32 v138, v138
	ds_read_b32 v137, v139
	ds_read_b32 v139, v140
	v_add_u32_e32 v140, 0xffffffb5, v217
	v_med3_i32 v141, v140, 0, v212
	v_max_i32_e32 v140, 0xffffffe0, v140
	v_add_u32_e32 v140, 32, v140
	v_min_u32_e32 v140, 0xc0, v140
	v_lshl_add_u32 v142, v140, 2, s15
	v_add_u32_e32 v140, 0xffffffb6, v217
	v_med3_i32 v143, v140, 0, v212
	v_max_i32_e32 v140, 0xffffffe0, v140
	v_add_u32_e32 v140, 32, v140
	v_min_u32_e32 v140, 0xc0, v140
	v_lshl_add_u32 v220, v140, 2, s15
	v_add_u32_e32 v140, 0xffffffb7, v217
	v_med3_i32 v221, v140, 0, v212
	v_max_i32_e32 v140, 0xffffffe0, v140
	v_add_u32_e32 v140, 32, v140
	v_min_u32_e32 v140, 0xc0, v140
	v_lshl_add_u32 v222, v140, 2, s15
	v_add_u32_e32 v140, 0xffffffb8, v217
	v_med3_i32 v223, v140, 0, v212
	v_max_i32_e32 v140, 0xffffffe0, v140
	v_add_u32_e32 v140, 32, v140
	v_min_u32_e32 v140, 0xc0, v140
	v_lshl_add_u32 v141, v141, 2, s15
	v_lshl_add_u32 v143, v143, 2, s15
	v_lshl_add_u32 v221, v221, 2, s15
	v_lshl_add_u32 v223, v223, 2, s15
	v_lshl_add_u32 v224, v140, 2, s15
	ds_read_b32 v140, v141
	ds_read_b32 v142, v142
	ds_read_b32 v141, v143
	ds_read_b32 v143, v220
	ds_read_b32 v220, v221
	ds_read_b32 v222, v222
	ds_read_b32 v221, v223
	ds_read_b32 v223, v224
	v_add_u32_e32 v224, 0xffffffbd, v217
	v_med3_i32 v225, v224, 0, v212
	v_max_i32_e32 v224, 0xffffffe0, v224
	v_add_u32_e32 v224, 32, v224
	v_min_u32_e32 v224, 0xc0, v224
	v_lshl_add_u32 v226, v224, 2, s15
	v_add_u32_e32 v224, 0xffffffbe, v217
	v_med3_i32 v227, v224, 0, v212
	v_max_i32_e32 v224, 0xffffffe0, v224
	v_add_u32_e32 v224, 32, v224
	v_min_u32_e32 v224, 0xc0, v224
	v_lshl_add_u32 v228, v224, 2, s15
	v_add_u32_e32 v224, 0xffffffbf, v217
	v_med3_i32 v229, v224, 0, v212
	v_max_i32_e32 v224, 0xffffffe0, v224
	v_add_u32_e32 v224, 32, v224
	v_min_u32_e32 v224, 0xc0, v224
	v_lshl_add_u32 v230, v224, 2, s15
	v_subrev_u32_e32 v224, 64, v217
	v_med3_i32 v231, v224, 0, v212
	v_max_i32_e32 v224, 0xffffffe0, v224
	v_add_u32_e32 v224, 32, v224
	v_lshl_add_u32 v225, v225, 2, s15
	v_lshl_add_u32 v227, v227, 2, s15
	v_lshl_add_u32 v229, v229, 2, s15
	v_lshl_add_u32 v231, v231, 2, s15
	v_min_u32_e32 v224, 0xc0, v224
	v_lshl_add_u32 v233, v224, 2, s15
	ds_read_b32 v224, v225
	ds_read_b32 v226, v226
	ds_read_b32 v225, v227
	ds_read_b32 v227, v228
	ds_read_b32 v228, v229
	ds_read_b32 v230, v230
	ds_read_b32 v229, v231
	ds_read_b32 v231, v233
	s_waitcnt lgkmcnt(5)
	v_pk_add_f32 v[108:109], v[108:109], v[224:225]
	s_waitcnt lgkmcnt(1)
	v_pk_add_f32 v[110:111], v[110:111], v[228:229]
	v_pk_add_f32 v[106:107], v[106:107], v[220:221]
	v_pk_add_f32 v[104:105], v[104:105], v[140:141]
	v_pk_add_f32 v[102:103], v[102:103], v[136:137]
	v_pk_add_f32 v[100:101], v[100:101], v[124:125]
	v_pk_add_f32 v[98:99], v[98:99], v[120:121]
	v_pk_add_f32 v[96:97], v[96:97], v[116:117]
	s_waitcnt lgkmcnt(0)
	v_pk_add_f32 v[94:95], v[94:95], v[230:231]
	v_pk_add_f32 v[92:93], v[92:93], v[226:227]
	v_pk_add_f32 v[90:91], v[90:91], v[222:223]
	v_pk_add_f32 v[88:89], v[88:89], v[142:143]
	v_pk_add_f32 v[86:87], v[86:87], v[138:139]
	v_pk_add_f32 v[84:85], v[84:85], v[126:127]
	v_pk_add_f32 v[82:83], v[82:83], v[122:123]
	v_pk_add_f32 v[80:81], v[80:81], v[118:119]
	s_branch .Lcm_done_A
; __device__ __forceinline__ void cmask(f32x16&p0,f32x16&p1,int jb,int qrel,int hi,lds_cfptr bt){
;     ...
;   for(int r=0;r<16;++r){const int ko=(r&3)+8*(r>>2);
;     const float b0=bt[med3i(base+ko,0,192)], b1=bt[med3i(base+ko+32,0,192)];
;     p0[r]=(ko>qlim)?NEG:p0[r]+b0; p1[r]=(ko+32>qlim)?NEG:p1[r]+b1;
.Lcm_masked_A:
	s_nop 7
	s_nop 3
	v_mov_b32_e32 v96, v213
	v_mov_b32_e32 v97, v213
	v_mov_b32_e32 v98, v213
	v_mov_b32_e32 v99, v213
	v_mov_b32_e32 v100, v213
	v_mov_b32_e32 v101, v213
	v_mov_b32_e32 v102, v213
	v_mov_b32_e32 v103, v213
	v_mov_b32_e32 v104, v213
	v_mov_b32_e32 v105, v213
	v_mov_b32_e32 v106, v213
	v_mov_b32_e32 v107, v213
	v_mov_b32_e32 v108, v213
	v_mov_b32_e32 v109, v213
	v_mov_b32_e32 v110, v213
	v_mov_b32_e32 v111, v213
	v_mov_b32_e32 v80, v213
	v_mov_b32_e32 v81, v213
	v_mov_b32_e32 v82, v213
	v_mov_b32_e32 v83, v213
	v_mov_b32_e32 v84, v213
	v_mov_b32_e32 v85, v213
	v_mov_b32_e32 v86, v213
	v_mov_b32_e32 v87, v213
	v_mov_b32_e32 v88, v213
	v_mov_b32_e32 v89, v213
	v_mov_b32_e32 v90, v213
	v_mov_b32_e32 v91, v213
	v_mov_b32_e32 v92, v213
	v_mov_b32_e32 v93, v213
	v_mov_b32_e32 v94, v213
	v_mov_b32_e32 v95, v213
.Lcm_done_A:
.LBB0_405:
	v_max_f32_e32 v116, v97, v97
	v_max_f32_e32 v117, v96, v96
	v_max_f32_e32 v116, v117, v116
	v_max3_f32 v117, v98, v99, v81
	v_max3_f32 v116, v116, v80, v82
	v_max3_f32 v116, v116, v83, v100
	v_max3_f32 v117, v117, v102, v103
	v_max3_f32 v116, v116, v101, v84
	v_max3_f32 v117, v117, v86, v87
	v_max3_f32 v116, v116, v85, v104
	v_max3_f32 v117, v117, v106, v107
	v_max3_f32 v116, v116, v105, v88
	v_max3_f32 v117, v117, v90, v91
	v_max3_f32 v116, v116, v89, v108
	v_max3_f32 v117, v117, v110, v111
	v_max3_f32 v116, v116, v109, v92
	v_max3_f32 v117, v117, v94, v95
	v_max3_f32 v116, v116, v93, v117
	v_mov_b32_e32 v117, v116
	s_nop 1
	v_permlane32_swap_b32_e32 v116, v117
	v_max_f32_e32 v117, v117, v117
	v_max_f32_e32 v116, v116, v116
	v_max_f32_e32 v116, v116, v117
	v_cmp_lt_f32_e32 vcc, s81, v116
	s_cmp_lg_u64 vcc, 0
	s_cselect_b64 s[50:51], -1, 0
	s_cbranch_vccnz .LBB0_435

; __device__ __forceinline__ void cmask(f32x16&p0,f32x16&p1,int jb,int qrel,int hi,lds_cfptr bt){
;     ...
;   const int kb=64*jb+4*hi; const int qlim=(qrel|63)-kb; const int base=kb-qrel+128;
;   #pragma unroll
;   for(int r=0;r<16;++r){const int ko=(r&3)+8*(r>>2);
;     const float b0=bt[med3i(base+ko,0,192)], b1=bt[med3i(base+ko+32,0,192)];
;     p0[r]=(ko>qlim)?NEG:p0[r]+b0; p1[r]=(ko+32>qlim)?NEG:p1[r]+b1;
;     if((r%CM_GRP)==CM_GRP-1)__builtin_amdgcn_sched_barrier(0); }
.LBB0_422:
	s_add_i32 s95, s95, 3
	s_lshl_b32 s95, s95, 6
	s_addk_i32 s95, 0x9a
	s_sub_i32 s95, s95, s57
	s_cmp_le_i32 s95, 0
	s_cbranch_scc1 .LBB0_424
	v_cmp_lt_i32_e32 vcc, -1, v218
	s_cbranch_vccz .Lcm_masked_B
	v_subrev_u32_e32 v194, 27, v217
	v_med3_i32 v195, v194, 0, v212
	v_max_i32_e32 v194, 0xffffffe0, v194
	v_add_u32_e32 v194, 32, v194
	v_min_u32_e32 v194, 0xc0, v194
	v_lshl_add_u32 v220, v194, 2, s15
	v_subrev_u32_e32 v194, 26, v217
	v_med3_i32 v221, v194, 0, v212
	v_max_i32_e32 v194, 0xffffffe0, v194
	v_add_u32_e32 v194, 32, v194
	v_min_u32_e32 v194, 0xc0, v194
	v_lshl_add_u32 v222, v194, 2, s15
	v_subrev_u32_e32 v194, 25, v217
	v_med3_i32 v223, v194, 0, v212
	v_max_i32_e32 v194, 0xffffffe0, v194
	v_add_u32_e32 v194, 32, v194
	v_min_u32_e32 v194, 0xc0, v194
	v_lshl_add_u32 v224, v194, 2, s15
	v_subrev_u32_e32 v194, 24, v217
	v_med3_i32 v225, v194, 0, v212
	v_max_i32_e32 v194, 0xffffffe0, v194
	v_add_u32_e32 v194, 32, v194
	v_min_u32_e32 v194, 0xc0, v194
	v_lshl_add_u32 v195, v195, 2, s15
	v_lshl_add_u32 v221, v221, 2, s15
	v_lshl_add_u32 v223, v223, 2, s15
	v_lshl_add_u32 v225, v225, 2, s15
	v_lshl_add_u32 v226, v194, 2, s15
	ds_read_b32 v194, v195
	ds_read_b32 v220, v220
	ds_read_b32 v195, v221
	ds_read_b32 v221, v222
	ds_read_b32 v222, v223
	ds_read_b32 v224, v224
	ds_read_b32 v223, v225
	ds_read_b32 v225, v226
	v_subrev_u32_e32 v226, 19, v217
	v_med3_i32 v227, v226, 0, v212
	v_max_i32_e32 v226, 0xffffffe0, v226
	v_add_u32_e32 v226, 32, v226
	v_min_u32_e32 v226, 0xc0, v226
	v_lshl_add_u32 v228, v226, 2, s15
	v_subrev_u32_e32 v226, 18, v217
	v_med3_i32 v229, v226, 0, v212
	v_max_i32_e32 v226, 0xffffffe0, v226
	v_add_u32_e32 v226, 32, v226
	v_min_u32_e32 v226, 0xc0, v226
	v_lshl_add_u32 v230, v226, 2, s15
	v_subrev_u32_e32 v226, 17, v217
	v_med3_i32 v231, v226, 0, v212
	v_max_i32_e32 v226, 0xffffffe0, v226
	v_add_u32_e32 v226, 32, v226
	v_min_u32_e32 v226, 0xc0, v226
	v_lshl_add_u32 v232, v226, 2, s15
	v_add_u32_e32 v226, -16, v217
	v_med3_i32 v233, v226, 0, v212
	v_max_i32_e32 v226, 0xffffffe0, v226
	v_add_u32_e32 v226, 32, v226
	v_min_u32_e32 v226, 0xc0, v226
	v_lshl_add_u32 v227, v227, 2, s15
	v_lshl_add_u32 v229, v229, 2, s15
	v_lshl_add_u32 v231, v231, 2, s15
	v_lshl_add_u32 v233, v233, 2, s15
	v_lshl_add_u32 v234, v226, 2, s15
	ds_read_b32 v226, v227
	ds_read_b32 v228, v228
	ds_read_b32 v227, v229
	ds_read_b32 v229, v230
	ds_read_b32 v230, v231
	ds_read_b32 v232, v232
	ds_read_b32 v231, v233
	ds_read_b32 v233, v234
	v_add_u32_e32 v234, -11, v217
	v_med3_i32 v235, v234, 0, v212
	v_max_i32_e32 v234, 0xffffffe0, v234
	v_add_u32_e32 v234, 32, v234
	v_min_u32_e32 v234, 0xc0, v234
	v_lshl_add_u32 v236, v234, 2, s15
	v_add_u32_e32 v234, -10, v217
	v_med3_i32 v237, v234, 0, v212
	v_max_i32_e32 v234, 0xffffffe0, v234
	v_add_u32_e32 v234, 32, v234
	v_min_u32_e32 v234, 0xc0, v234
	v_lshl_add_u32 v238, v234, 2, s15
	v_add_u32_e32 v234, -9, v217
	v_med3_i32 v239, v234, 0, v212
	v_max_i32_e32 v234, 0xffffffe0, v234
	v_add_u32_e32 v234, 32, v234
	v_min_u32_e32 v234, 0xc0, v234
	v_lshl_add_u32 v240, v234, 2, s15
	v_add_u32_e32 v234, -8, v217
	v_med3_i32 v241, v234, 0, v212
	v_max_i32_e32 v234, 0xffffffe0, v234
	v_add_u32_e32 v234, 32, v234
	v_min_u32_e32 v234, 0xc0, v234
	v_lshl_add_u32 v235, v235, 2, s15
	v_lshl_add_u32 v237, v237, 2, s15
	v_lshl_add_u32 v239, v239, 2, s15
	v_lshl_add_u32 v241, v241, 2, s15
	v_lshl_add_u32 v242, v234, 2, s15
	ds_read_b32 v234, v235
	ds_read_b32 v236, v236
	ds_read_b32 v235, v237
	ds_read_b32 v237, v238
	ds_read_b32 v238, v239
	ds_read_b32 v240, v240
	ds_read_b32 v239, v241
	ds_read_b32 v241, v242
	v_add_u32_e32 v242, -3, v217
	v_med3_i32 v243, v242, 0, v212
	v_max_i32_e32 v242, 0xffffffe0, v242
	v_add_u32_e32 v242, 32, v242
	v_min_u32_e32 v242, 0xc0, v242
	v_lshl_add_u32 v244, v242, 2, s15
	v_add_u32_e32 v242, -2, v217
	v_med3_i32 v245, v242, 0, v212
	v_max_i32_e32 v242, 0xffffffe0, v242
	v_add_u32_e32 v242, 32, v242
	v_min_u32_e32 v242, 0xc0, v242
	v_lshl_add_u32 v246, v242, 2, s15
	v_add_u32_e32 v242, -1, v217
	v_med3_i32 v247, v242, 0, v212
	v_max_i32_e32 v242, 0xffffffe0, v242
	v_add_u32_e32 v242, 32, v242
	v_min_u32_e32 v242, 0xc0, v242
	v_lshl_add_u32 v248, v242, 2, s15
	v_med3_i32 v242, v217, 0, v212
	v_lshl_add_u32 v249, v242, 2, s15
	v_max_i32_e32 v242, 0xffffffe0, v217
	v_add_u32_e32 v242, 32, v242
	v_lshl_add_u32 v243, v243, 2, s15
	v_lshl_add_u32 v245, v245, 2, s15
	v_lshl_add_u32 v247, v247, 2, s15
	v_min_u32_e32 v242, 0xc0, v242
	v_lshl_add_u32 v250, v242, 2, s15
	ds_read_b32 v242, v243
	ds_read_b32 v244, v244
	ds_read_b32 v243, v245
	ds_read_b32 v245, v246
	ds_read_b32 v246, v247
	ds_read_b32 v248, v248
	ds_read_b32 v247, v249
	ds_read_b32 v249, v250
	s_waitcnt lgkmcnt(5)
	v_pk_add_f32 v[140:141], v[140:141], v[242:243]
	v_pk_add_f32 v[138:139], v[138:139], v[238:239]
	s_waitcnt lgkmcnt(1)
	v_pk_add_f32 v[142:143], v[142:143], v[246:247]
	v_pk_add_f32 v[136:137], v[136:137], v[234:235]
	v_pk_add_f32 v[134:135], v[134:135], v[230:231]
	v_pk_add_f32 v[132:133], v[132:133], v[226:227]
	v_pk_add_f32 v[130:131], v[130:131], v[222:223]
	v_pk_add_f32 v[128:129], v[128:129], v[194:195]
	s_waitcnt lgkmcnt(0)
	v_pk_add_f32 v[126:127], v[126:127], v[248:249]
	v_pk_add_f32 v[124:125], v[124:125], v[244:245]
	v_pk_add_f32 v[122:123], v[122:123], v[240:241]
	v_pk_add_f32 v[120:121], v[120:121], v[236:237]
	v_pk_add_f32 v[118:119], v[118:119], v[232:233]
	v_pk_add_f32 v[116:117], v[116:117], v[228:229]
	v_pk_add_f32 v[114:115], v[114:115], v[224:225]
	v_pk_add_f32 v[112:113], v[112:113], v[220:221]
	s_branch .Lcm_done_B
; __device__ __forceinline__ void cmask(f32x16&p0,f32x16&p1,int jb,int qrel,int hi,lds_cfptr bt){
;     ...
;   for(int r=0;r<16;++r){const int ko=(r&3)+8*(r>>2);
;     const float b0=bt[med3i(base+ko,0,192)], b1=bt[med3i(base+ko+32,0,192)];
;     p0[r]=(ko>qlim)?NEG:p0[r]+b0; p1[r]=(ko+32>qlim)?NEG:p1[r]+b1;
.Lcm_masked_B:
	s_nop 7
	s_nop 3
	v_mov_b32_e32 v112, v213
	v_mov_b32_e32 v113, v213
	v_mov_b32_e32 v114, v213
	v_mov_b32_e32 v115, v213
	v_mov_b32_e32 v116, v213
	v_mov_b32_e32 v117, v213
	v_mov_b32_e32 v118, v213
	v_mov_b32_e32 v119, v213
	v_mov_b32_e32 v120, v213
	v_mov_b32_e32 v121, v213
	v_mov_b32_e32 v122, v213
	v_mov_b32_e32 v123, v213
	v_mov_b32_e32 v124, v213
	v_mov_b32_e32 v125, v213
	v_mov_b32_e32 v126, v213
	v_mov_b32_e32 v127, v213
	v_mov_b32_e32 v128, v213
	v_mov_b32_e32 v129, v213
	v_mov_b32_e32 v130, v213
	v_mov_b32_e32 v131, v213
	v_mov_b32_e32 v132, v213
	v_mov_b32_e32 v133, v213
	v_mov_b32_e32 v134, v213
	v_mov_b32_e32 v135, v213
	v_mov_b32_e32 v136, v213
	v_mov_b32_e32 v137, v213
	v_mov_b32_e32 v138, v213
	v_mov_b32_e32 v139, v213
	v_mov_b32_e32 v140, v213
	v_mov_b32_e32 v141, v213
	v_mov_b32_e32 v142, v213
	v_mov_b32_e32 v143, v213
.Lcm_done_B:
.LBB0_424:
	v_add_f32_e32 v192, v192, v193
	v_max_f32_e32 v193, v129, v129
	v_max_f32_e32 v194, v128, v128
	v_max_f32_e32 v193, v194, v193
	v_max3_f32 v194, v130, v131, v113
	v_max3_f32 v193, v193, v112, v114
	v_max3_f32 v193, v193, v115, v132
	v_max3_f32 v194, v194, v134, v135
	v_max3_f32 v193, v193, v133, v116
	v_max3_f32 v194, v194, v118, v119
	v_max3_f32 v193, v193, v117, v136
	v_max3_f32 v194, v194, v138, v139
	v_max3_f32 v193, v193, v137, v120
	v_max3_f32 v194, v194, v122, v123
	v_max3_f32 v193, v193, v121, v140
	v_max3_f32 v194, v194, v142, v143
	v_max3_f32 v193, v193, v141, v124
	v_max3_f32 v194, v194, v126, v127
	v_max3_f32 v193, v193, v125, v194
	v_mov_b32_e32 v194, v193
	s_nop 1
	v_permlane32_swap_b32_e32 v193, v194
	v_max_f32_e32 v194, v194, v194
	v_max_f32_e32 v193, v193, v193
	v_max_f32_e32 v193, v193, v194
	v_cmp_lt_f32_e32 vcc, s81, v193
	s_cmp_lg_u64 vcc, 0
	v_add_f32_e32 v192, v203, v192
	s_cselect_b64 s[44:45], -1, 0
	s_cbranch_vccnz .LBB0_438

; __device__ __forceinline__ u32x4 pack8(f32x4 v0, f32x4 v1) { u32x4 w; w.x = cvt_pk_bf16(v0[0], v0[1]); w.y = cvt_pk_bf16(v0[2], v0[3]); w.z = cvt_pk_bf16(v1[0], v1[1]); w.w = cvt_pk_bf16(v1[2], v1[3]); return w; }
;     __device__ __forceinline__ void operator()(const f32x4 (&acc)[2][2][4][2], const Unit& u, int wr, int wc, int fr, int fq) const {
;     ...
;                         f32x4 b0, b1;
;                         if (xp) { const float* src = xp + (size_t)row * 2048 + col; b0 = *(const f32x4*)src; b1 = *(const f32x4*)(src + 4); }
;                         else { const u32x4 w = *(const u32x4*)(baseb + (size_t)row * 2048 + col);
;                             b0 = (f32x4){__builtin_bit_cast(float, w.x << 16), __builtin_bit_cast(float, w.x & 0xffff0000u), __builtin_bit_cast(float, w.y << 16), __builtin_bit_cast(float, w.y & 0xffff0000u)};
;                             b1 = (f32x4){__builtin_bit_cast(float, w.z << 16), __builtin_bit_cast(float, w.z & 0xffff0000u), __builtin_bit_cast(float, w.w << 16), __builtin_bit_cast(float, w.w & 0xffff0000u)}; }
;                         *(u32x4*)(outb + (size_t)row * 2048 + col) = pack8(b0 + g[bj][0] * acc[ai][bj][m][0], b1 + g[bj][1] * acc[ai][bj][m][1]); } } }
.LBB0_785:
	v_lshl_add_u64 v[176:177], s[14:15], 0, v[162:163]
	v_lshlrev_b64 v[180:181], 1, v[158:159]
	v_lshl_add_u64 v[176:177], v[176:177], 0, v[180:181]
	s_nop 0
	v_lshl_add_u64 v[182:183], s[62:63], 0, v[162:163]
	s_waitcnt vmcnt(7)
	v_lshlrev_b32_e32 v184, 16, v188
	v_and_b32_e32 v185, 0xffff0000, v188
	v_lshlrev_b32_e32 v176, 16, v189
	v_and_b32_e32 v177, 0xffff0000, v189
	v_lshlrev_b32_e32 v186, 16, v190
	v_and_b32_e32 v187, 0xffff0000, v190
	v_lshlrev_b32_e32 v178, 16, v191
	v_and_b32_e32 v179, 0xffff0000, v191
	v_pk_fma_f32 v[140:141], v[140:141], v[132:133], v[184:185]
	v_pk_fma_f32 v[142:143], v[142:143], v[134:135], v[176:177]
	v_pk_fma_f32 v[176:177], v[138:139], v[130:131], v[178:179]
	v_pk_fma_f32 v[138:139], v[136:137], v[128:129], v[186:187]
	v_cvt_pk_bf16_f32 v136, v140, v141
	v_lshl_add_u64 v[140:141], v[182:183], 0, v[180:181]
	v_cvt_pk_bf16_f32 v137, v142, v143
	v_cvt_pk_bf16_f32 v138, v138, v139
	v_cvt_pk_bf16_f32 v139, v176, v177
	global_store_dwordx4 v[140:141], v[136:139], off

; __device__ __forceinline__ u32x4 pack8(f32x4 v0, f32x4 v1) { u32x4 w; w.x = cvt_pk_bf16(v0[0], v0[1]); w.y = cvt_pk_bf16(v0[2], v0[3]); w.z = cvt_pk_bf16(v1[0], v1[1]); w.w = cvt_pk_bf16(v1[2], v1[3]); return w; }
;     __device__ __forceinline__ void operator()(const f32x4 (&acc)[2][2][4][2], const Unit& u, int wr, int wc, int fr, int fq) const {
;     ...
;                         f32x4 b0, b1;
;                         if (xp) { const float* src = xp + (size_t)row * 2048 + col; b0 = *(const f32x4*)src; b1 = *(const f32x4*)(src + 4); }
;                         else { const u32x4 w = *(const u32x4*)(baseb + (size_t)row * 2048 + col);
;                             b0 = (f32x4){__builtin_bit_cast(float, w.x << 16), __builtin_bit_cast(float, w.x & 0xffff0000u), __builtin_bit_cast(float, w.y << 16), __builtin_bit_cast(float, w.y & 0xffff0000u)};
;                             b1 = (f32x4){__builtin_bit_cast(float, w.z << 16), __builtin_bit_cast(float, w.z & 0xffff0000u), __builtin_bit_cast(float, w.w << 16), __builtin_bit_cast(float, w.w & 0xffff0000u)}; }
;                         *(u32x4*)(outb + (size_t)row * 2048 + col) = pack8(b0 + g[bj][0] * acc[ai][bj][m][0], b1 + g[bj][1] * acc[ai][bj][m][1]); } } }
.LBB0_788:
	s_nop 0
	v_lshl_add_u64 v[136:137], s[14:15], 0, v[162:163]
	v_lshlrev_b64 v[140:141], 1, v[158:159]
	v_lshl_add_u64 v[136:137], v[136:137], 0, v[140:141]
	s_nop 0
	v_lshl_add_u64 v[142:143], s[62:63], 0, v[162:163]
	s_waitcnt vmcnt(7)
	v_lshlrev_b32_e32 v162, 16, v192
	v_and_b32_e32 v163, 0xffff0000, v192
	v_lshlrev_b32_e32 v136, 16, v193
	v_and_b32_e32 v137, 0xffff0000, v193
	v_lshlrev_b32_e32 v164, 16, v194
	v_and_b32_e32 v165, 0xffff0000, v194
	v_lshlrev_b32_e32 v138, 16, v195
	v_and_b32_e32 v139, 0xffff0000, v195
	v_pk_fma_f32 v[124:125], v[124:125], v[116:117], v[162:163]
	v_pk_fma_f32 v[126:127], v[126:127], v[118:119], v[136:137]
	v_pk_fma_f32 v[136:137], v[122:123], v[114:115], v[138:139]
	v_pk_fma_f32 v[122:123], v[120:121], v[112:113], v[164:165]
	v_cvt_pk_bf16_f32 v120, v124, v125
	v_lshl_add_u64 v[124:125], v[142:143], 0, v[140:141]
	v_cvt_pk_bf16_f32 v121, v126, v127
	v_cvt_pk_bf16_f32 v122, v122, v123
	v_cvt_pk_bf16_f32 v123, v136, v137
	global_store_dwordx4 v[124:125], v[120:123], off offset:256

;     __device__ __forceinline__ void operator()(const f32x4 (&acc)[2][2][4][2], const Unit& u, int wr, int wc, int fr, int fq) const {
;     ...
;             for (int m = 0; m < 4; ++m) { const int row = row0 + ai * HALF + m * 16;
; #pragma unroll
;                 for (int bj = 0; bj < 2; ++bj) { const int col = col0 + bj * HALF;
;                     if (u.split) { float* pp = part + ((size_t)(u.k0 / u.nt) * (MROWS - MP) + (size_t)(row - MP)) * 2048 + col;
;                         *(f32x4*)pp = g[bj][0] * acc[ai][bj][m][0]; *(f32x4*)(pp + 4) = g[bj][1] * acc[ai][bj][m][1];
;                     } else {
;                         f32x4 b0, b1;
;                         if (xp) { const float* src = xp + (size_t)row * 2048 + col; b0 = *(const f32x4*)src; b1 = *(const f32x4*)(src + 4); }
;                         else { const u32x4 w = *(const u32x4*)(baseb + (size_t)row * 2048 + col);
.LBB0_791:
	v_lshlrev_b64 v[162:163], 12, v[160:161]
	v_lshl_add_u64 v[222:223], s[14:15], 0, v[162:163]
	v_lshlrev_b64 v[224:225], 1, v[158:159]
	v_lshl_add_u64 v[222:223], v[222:223], 0, v[224:225]
	global_load_dwordx4 v[188:191], v[222:223], off
	global_load_dwordx4 v[192:195], v[222:223], off offset:256
	v_add_co_u32_e32 v224, vcc, 0x10000, v222
	s_nop 1
	v_addc_co_u32_e32 v225, vcc, 0, v223, vcc
	global_load_dwordx4 v[196:199], v[224:225], off
	global_load_dwordx4 v[200:203], v[224:225], off offset:256
	v_add_co_u32_e32 v226, vcc, 0x20000, v222
	s_nop 1
	v_addc_co_u32_e32 v227, vcc, 0, v223, vcc
	global_load_dwordx4 v[204:207], v[226:227], off
	global_load_dwordx4 v[208:211], v[226:227], off offset:256
	v_add_co_u32_e32 v228, vcc, 0x30000, v222
	s_nop 1
	v_addc_co_u32_e32 v229, vcc, 0, v223, vcc
	global_load_dwordx4 v[212:215], v[228:229], off
	global_load_dwordx4 v[216:219], v[228:229], off offset:256
	s_branch .LBB0_785

; __device__ __forceinline__ u32x4 pack8(f32x4 v0, f32x4 v1) { u32x4 w; w.x = cvt_pk_bf16(v0[0], v0[1]); w.y = cvt_pk_bf16(v0[2], v0[3]); w.z = cvt_pk_bf16(v1[0], v1[1]); w.w = cvt_pk_bf16(v1[2], v1[3]); return w; }
;     __device__ __forceinline__ void operator()(const f32x4 (&acc)[2][2][4][2], const Unit& u, int wr, int wc, int fr, int fq) const {
;     ...
;                         f32x4 b0, b1;
;                         if (xp) { const float* src = xp + (size_t)row * 2048 + col; b0 = *(const f32x4*)src; b1 = *(const f32x4*)(src + 4); }
;                         else { const u32x4 w = *(const u32x4*)(baseb + (size_t)row * 2048 + col);
;                             b0 = (f32x4){__builtin_bit_cast(float, w.x << 16), __builtin_bit_cast(float, w.x & 0xffff0000u), __builtin_bit_cast(float, w.y << 16), __builtin_bit_cast(float, w.y & 0xffff0000u)};
;                             b1 = (f32x4){__builtin_bit_cast(float, w.z << 16), __builtin_bit_cast(float, w.z & 0xffff0000u), __builtin_bit_cast(float, w.w << 16), __builtin_bit_cast(float, w.w & 0xffff0000u)}; }
;                         *(u32x4*)(outb + (size_t)row * 2048 + col) = pack8(b0 + g[bj][0] * acc[ai][bj][m][0], b1 + g[bj][1] * acc[ai][bj][m][1]); } } }
.LBB0_794:
	v_or_b32_e32 v120, 16, v160
	v_ashrrev_i32_e32 v121, 31, v120
	s_andn2_b64 vcc, exec, s[58:59]
	v_lshlrev_b64 v[120:121], 12, v[120:121]
	s_cbranch_vccnz .LBB0_796
	v_lshl_add_u64 v[124:125], s[14:15], 0, v[120:121]
	v_lshlrev_b64 v[136:137], 1, v[158:159]
	v_lshl_add_u64 v[124:125], v[124:125], 0, v[136:137]
	s_nop 0
	v_lshl_add_u64 v[138:139], s[62:63], 0, v[120:121]
	s_waitcnt vmcnt(7)
	v_lshlrev_b32_e32 v140, 16, v196
	v_and_b32_e32 v141, 0xffff0000, v196
	v_lshlrev_b32_e32 v124, 16, v197
	v_and_b32_e32 v125, 0xffff0000, v197
	v_lshlrev_b32_e32 v142, 16, v198
	v_and_b32_e32 v143, 0xffff0000, v198
	v_lshlrev_b32_e32 v126, 16, v199
	v_and_b32_e32 v127, 0xffff0000, v199
	v_pk_fma_f32 v[108:109], v[108:109], v[132:133], v[140:141]
	v_pk_fma_f32 v[110:111], v[110:111], v[134:135], v[124:125]
	v_pk_fma_f32 v[124:125], v[106:107], v[130:131], v[126:127]
	v_pk_fma_f32 v[106:107], v[104:105], v[128:129], v[142:143]
	v_cvt_pk_bf16_f32 v104, v108, v109
	v_lshl_add_u64 v[108:109], v[138:139], 0, v[136:137]
	v_cvt_pk_bf16_f32 v105, v110, v111
	v_cvt_pk_bf16_f32 v106, v106, v107
	v_cvt_pk_bf16_f32 v107, v124, v125
	global_store_dwordx4 v[108:109], v[104:107], off

; __device__ __forceinline__ u32x4 pack8(f32x4 v0, f32x4 v1) { u32x4 w; w.x = cvt_pk_bf16(v0[0], v0[1]); w.y = cvt_pk_bf16(v0[2], v0[3]); w.z = cvt_pk_bf16(v1[0], v1[1]); w.w = cvt_pk_bf16(v1[2], v1[3]); return w; }
;     __device__ __forceinline__ void operator()(const f32x4 (&acc)[2][2][4][2], const Unit& u, int wr, int wc, int fr, int fq) const {
;     ...
;                         f32x4 b0, b1;
;                         if (xp) { const float* src = xp + (size_t)row * 2048 + col; b0 = *(const f32x4*)src; b1 = *(const f32x4*)(src + 4); }
;                         else { const u32x4 w = *(const u32x4*)(baseb + (size_t)row * 2048 + col);
;                             b0 = (f32x4){__builtin_bit_cast(float, w.x << 16), __builtin_bit_cast(float, w.x & 0xffff0000u), __builtin_bit_cast(float, w.y << 16), __builtin_bit_cast(float, w.y & 0xffff0000u)};
;                             b1 = (f32x4){__builtin_bit_cast(float, w.z << 16), __builtin_bit_cast(float, w.z & 0xffff0000u), __builtin_bit_cast(float, w.w << 16), __builtin_bit_cast(float, w.w & 0xffff0000u)}; }
;                         *(u32x4*)(outb + (size_t)row * 2048 + col) = pack8(b0 + g[bj][0] * acc[ai][bj][m][0], b1 + g[bj][1] * acc[ai][bj][m][1]); } } }
.LBB0_798:
	s_nop 0
	v_lshl_add_u64 v[104:105], s[14:15], 0, v[120:121]
	v_lshlrev_b64 v[108:109], 1, v[158:159]
	v_lshl_add_u64 v[104:105], v[104:105], 0, v[108:109]
	s_nop 0
	v_lshl_add_u64 v[110:111], s[62:63], 0, v[120:121]
	s_waitcnt vmcnt(7)
	v_lshlrev_b32_e32 v120, 16, v200
	v_and_b32_e32 v121, 0xffff0000, v200
	v_lshlrev_b32_e32 v104, 16, v201
	v_and_b32_e32 v105, 0xffff0000, v201
	v_lshlrev_b32_e32 v122, 16, v202
	v_and_b32_e32 v123, 0xffff0000, v202
	v_lshlrev_b32_e32 v106, 16, v203
	v_and_b32_e32 v107, 0xffff0000, v203
	v_pk_fma_f32 v[100:101], v[100:101], v[116:117], v[120:121]
	v_pk_fma_f32 v[102:103], v[102:103], v[118:119], v[104:105]
	v_pk_fma_f32 v[104:105], v[98:99], v[114:115], v[106:107]
	v_pk_fma_f32 v[98:99], v[96:97], v[112:113], v[122:123]
	v_cvt_pk_bf16_f32 v96, v100, v101
	v_lshl_add_u64 v[100:101], v[110:111], 0, v[108:109]
	v_cvt_pk_bf16_f32 v97, v102, v103
	v_cvt_pk_bf16_f32 v98, v98, v99
	v_cvt_pk_bf16_f32 v99, v104, v105
	global_store_dwordx4 v[100:101], v[96:99], off offset:256

; __device__ __forceinline__ u32x4 pack8(f32x4 v0, f32x4 v1) { u32x4 w; w.x = cvt_pk_bf16(v0[0], v0[1]); w.y = cvt_pk_bf16(v0[2], v0[3]); w.z = cvt_pk_bf16(v1[0], v1[1]); w.w = cvt_pk_bf16(v1[2], v1[3]); return w; }
;     __device__ __forceinline__ void operator()(const f32x4 (&acc)[2][2][4][2], const Unit& u, int wr, int wc, int fr, int fq) const {
;     ...
;                         f32x4 b0, b1;
;                         if (xp) { const float* src = xp + (size_t)row * 2048 + col; b0 = *(const f32x4*)src; b1 = *(const f32x4*)(src + 4); }
;                         else { const u32x4 w = *(const u32x4*)(baseb + (size_t)row * 2048 + col);
;                             b0 = (f32x4){__builtin_bit_cast(float, w.x << 16), __builtin_bit_cast(float, w.x & 0xffff0000u), __builtin_bit_cast(float, w.y << 16), __builtin_bit_cast(float, w.y & 0xffff0000u)};
;                             b1 = (f32x4){__builtin_bit_cast(float, w.z << 16), __builtin_bit_cast(float, w.z & 0xffff0000u), __builtin_bit_cast(float, w.w << 16), __builtin_bit_cast(float, w.w & 0xffff0000u)}; }
;                         *(u32x4*)(outb + (size_t)row * 2048 + col) = pack8(b0 + g[bj][0] * acc[ai][bj][m][0], b1 + g[bj][1] * acc[ai][bj][m][1]); } } }
.LBB0_803:
	v_or_b32_e32 v96, 32, v160
	v_ashrrev_i32_e32 v97, 31, v96
	s_andn2_b64 vcc, exec, s[58:59]
	v_lshlrev_b64 v[96:97], 12, v[96:97]
	s_cbranch_vccnz .LBB0_805
	v_lshl_add_u64 v[100:101], s[14:15], 0, v[96:97]
	v_lshlrev_b64 v[104:105], 1, v[158:159]
	v_lshl_add_u64 v[100:101], v[100:101], 0, v[104:105]
	s_nop 0
	v_lshl_add_u64 v[106:107], s[62:63], 0, v[96:97]
	s_waitcnt vmcnt(7)
	v_lshlrev_b32_e32 v108, 16, v204
	v_and_b32_e32 v109, 0xffff0000, v204
	v_lshlrev_b32_e32 v100, 16, v205
	v_and_b32_e32 v101, 0xffff0000, v205
	v_lshlrev_b32_e32 v110, 16, v206
	v_and_b32_e32 v111, 0xffff0000, v206
	v_lshlrev_b32_e32 v102, 16, v207
	v_and_b32_e32 v103, 0xffff0000, v207
	v_pk_fma_f32 v[92:93], v[92:93], v[132:133], v[108:109]
	v_pk_fma_f32 v[94:95], v[94:95], v[134:135], v[100:101]
	v_pk_fma_f32 v[100:101], v[90:91], v[130:131], v[102:103]
	v_pk_fma_f32 v[90:91], v[88:89], v[128:129], v[110:111]
	v_cvt_pk_bf16_f32 v88, v92, v93
	v_lshl_add_u64 v[92:93], v[106:107], 0, v[104:105]
	v_cvt_pk_bf16_f32 v89, v94, v95
	v_cvt_pk_bf16_f32 v90, v90, v91
	v_cvt_pk_bf16_f32 v91, v100, v101
	global_store_dwordx4 v[92:93], v[88:91], off

; __device__ __forceinline__ u32x4 pack8(f32x4 v0, f32x4 v1) { u32x4 w; w.x = cvt_pk_bf16(v0[0], v0[1]); w.y = cvt_pk_bf16(v0[2], v0[3]); w.z = cvt_pk_bf16(v1[0], v1[1]); w.w = cvt_pk_bf16(v1[2], v1[3]); return w; }
;     __device__ __forceinline__ void operator()(const f32x4 (&acc)[2][2][4][2], const Unit& u, int wr, int wc, int fr, int fq) const {
;     ...
;                         f32x4 b0, b1;
;                         if (xp) { const float* src = xp + (size_t)row * 2048 + col; b0 = *(const f32x4*)src; b1 = *(const f32x4*)(src + 4); }
;                         else { const u32x4 w = *(const u32x4*)(baseb + (size_t)row * 2048 + col);
;                             b0 = (f32x4){__builtin_bit_cast(float, w.x << 16), __builtin_bit_cast(float, w.x & 0xffff0000u), __builtin_bit_cast(float, w.y << 16), __builtin_bit_cast(float, w.y & 0xffff0000u)};
;                             b1 = (f32x4){__builtin_bit_cast(float, w.z << 16), __builtin_bit_cast(float, w.z & 0xffff0000u), __builtin_bit_cast(float, w.w << 16), __builtin_bit_cast(float, w.w & 0xffff0000u)}; }
;                         *(u32x4*)(outb + (size_t)row * 2048 + col) = pack8(b0 + g[bj][0] * acc[ai][bj][m][0], b1 + g[bj][1] * acc[ai][bj][m][1]); } } }
.LBB0_807:
	s_nop 0
	v_lshl_add_u64 v[88:89], s[14:15], 0, v[96:97]
	v_lshlrev_b64 v[92:93], 1, v[158:159]
	v_lshl_add_u64 v[88:89], v[88:89], 0, v[92:93]
	s_nop 0
	v_lshl_add_u64 v[94:95], s[62:63], 0, v[96:97]
	s_waitcnt vmcnt(7)
	v_lshlrev_b32_e32 v96, 16, v208
	v_and_b32_e32 v97, 0xffff0000, v208
	v_lshlrev_b32_e32 v88, 16, v209
	v_and_b32_e32 v89, 0xffff0000, v209
	v_lshlrev_b32_e32 v98, 16, v210
	v_and_b32_e32 v99, 0xffff0000, v210
	v_lshlrev_b32_e32 v90, 16, v211
	v_and_b32_e32 v91, 0xffff0000, v211
	v_pk_fma_f32 v[84:85], v[84:85], v[116:117], v[96:97]
	v_pk_fma_f32 v[86:87], v[86:87], v[118:119], v[88:89]
	v_pk_fma_f32 v[88:89], v[82:83], v[114:115], v[90:91]
	v_pk_fma_f32 v[82:83], v[80:81], v[112:113], v[98:99]
	v_cvt_pk_bf16_f32 v80, v84, v85
	v_lshl_add_u64 v[84:85], v[94:95], 0, v[92:93]
	v_cvt_pk_bf16_f32 v81, v86, v87
	v_cvt_pk_bf16_f32 v82, v82, v83
	v_cvt_pk_bf16_f32 v83, v88, v89
	global_store_dwordx4 v[84:85], v[80:83], off offset:256

; __device__ __forceinline__ u32x4 pack8(f32x4 v0, f32x4 v1) { u32x4 w; w.x = cvt_pk_bf16(v0[0], v0[1]); w.y = cvt_pk_bf16(v0[2], v0[3]); w.z = cvt_pk_bf16(v1[0], v1[1]); w.w = cvt_pk_bf16(v1[2], v1[3]); return w; }
;     __device__ __forceinline__ void operator()(const f32x4 (&acc)[2][2][4][2], const Unit& u, int wr, int wc, int fr, int fq) const {
;     ...
;                         f32x4 b0, b1;
;                         if (xp) { const float* src = xp + (size_t)row * 2048 + col; b0 = *(const f32x4*)src; b1 = *(const f32x4*)(src + 4); }
;                         else { const u32x4 w = *(const u32x4*)(baseb + (size_t)row * 2048 + col);
;                             b0 = (f32x4){__builtin_bit_cast(float, w.x << 16), __builtin_bit_cast(float, w.x & 0xffff0000u), __builtin_bit_cast(float, w.y << 16), __builtin_bit_cast(float, w.y & 0xffff0000u)};
;                             b1 = (f32x4){__builtin_bit_cast(float, w.z << 16), __builtin_bit_cast(float, w.z & 0xffff0000u), __builtin_bit_cast(float, w.w << 16), __builtin_bit_cast(float, w.w & 0xffff0000u)}; }
;                         *(u32x4*)(outb + (size_t)row * 2048 + col) = pack8(b0 + g[bj][0] * acc[ai][bj][m][0], b1 + g[bj][1] * acc[ai][bj][m][1]); } } }
.LBB0_812:
	v_or_b32_e32 v80, 48, v160
	v_ashrrev_i32_e32 v81, 31, v80
	s_andn2_b64 vcc, exec, s[58:59]
	v_lshlrev_b64 v[80:81], 12, v[80:81]
	s_cbranch_vccnz .LBB0_814
	v_lshl_add_u64 v[84:85], s[14:15], 0, v[80:81]
	v_lshlrev_b64 v[88:89], 1, v[158:159]
	v_lshl_add_u64 v[84:85], v[84:85], 0, v[88:89]
	s_nop 0
	v_lshl_add_u64 v[90:91], s[62:63], 0, v[80:81]
	s_waitcnt vmcnt(7)
	v_lshlrev_b32_e32 v92, 16, v212
	v_and_b32_e32 v93, 0xffff0000, v212
	v_lshlrev_b32_e32 v84, 16, v213
	v_and_b32_e32 v85, 0xffff0000, v213
	v_lshlrev_b32_e32 v94, 16, v214
	v_and_b32_e32 v95, 0xffff0000, v214
	v_lshlrev_b32_e32 v86, 16, v215
	v_and_b32_e32 v87, 0xffff0000, v215
	v_pk_fma_f32 v[76:77], v[76:77], v[132:133], v[92:93]
	v_pk_fma_f32 v[78:79], v[78:79], v[134:135], v[84:85]
	v_pk_fma_f32 v[84:85], v[74:75], v[130:131], v[86:87]
	v_pk_fma_f32 v[74:75], v[72:73], v[128:129], v[94:95]
	v_cvt_pk_bf16_f32 v72, v76, v77
	v_lshl_add_u64 v[76:77], v[90:91], 0, v[88:89]
	v_cvt_pk_bf16_f32 v73, v78, v79
	v_cvt_pk_bf16_f32 v74, v74, v75
	v_cvt_pk_bf16_f32 v75, v84, v85
	global_store_dwordx4 v[76:77], v[72:75], off

; __device__ __forceinline__ u32x4 pack8(f32x4 v0, f32x4 v1) { u32x4 w; w.x = cvt_pk_bf16(v0[0], v0[1]); w.y = cvt_pk_bf16(v0[2], v0[3]); w.z = cvt_pk_bf16(v1[0], v1[1]); w.w = cvt_pk_bf16(v1[2], v1[3]); return w; }
;     __device__ __forceinline__ void operator()(const f32x4 (&acc)[2][2][4][2], const Unit& u, int wr, int wc, int fr, int fq) const {
;     ...
;                         f32x4 b0, b1;
;                         if (xp) { const float* src = xp + (size_t)row * 2048 + col; b0 = *(const f32x4*)src; b1 = *(const f32x4*)(src + 4); }
;                         else { const u32x4 w = *(const u32x4*)(baseb + (size_t)row * 2048 + col);
;                             b0 = (f32x4){__builtin_bit_cast(float, w.x << 16), __builtin_bit_cast(float, w.x & 0xffff0000u), __builtin_bit_cast(float, w.y << 16), __builtin_bit_cast(float, w.y & 0xffff0000u)};
;                             b1 = (f32x4){__builtin_bit_cast(float, w.z << 16), __builtin_bit_cast(float, w.z & 0xffff0000u), __builtin_bit_cast(float, w.w << 16), __builtin_bit_cast(float, w.w & 0xffff0000u)}; }
;                         *(u32x4*)(outb + (size_t)row * 2048 + col) = pack8(b0 + g[bj][0] * acc[ai][bj][m][0], b1 + g[bj][1] * acc[ai][bj][m][1]); } } }
.LBB0_816:
	s_nop 0
	v_lshl_add_u64 v[72:73], s[14:15], 0, v[80:81]
	v_lshlrev_b64 v[76:77], 1, v[158:159]
	v_lshl_add_u64 v[72:73], v[72:73], 0, v[76:77]
	s_nop 0
	v_lshl_add_u64 v[78:79], s[62:63], 0, v[80:81]
	s_waitcnt vmcnt(7)
	v_lshlrev_b32_e32 v80, 16, v216
	v_and_b32_e32 v81, 0xffff0000, v216
	v_lshlrev_b32_e32 v72, 16, v217
	v_and_b32_e32 v73, 0xffff0000, v217
	v_lshlrev_b32_e32 v82, 16, v218
	v_and_b32_e32 v83, 0xffff0000, v218
	v_lshlrev_b32_e32 v74, 16, v219
	v_and_b32_e32 v75, 0xffff0000, v219
	v_pk_fma_f32 v[68:69], v[68:69], v[116:117], v[80:81]
	v_pk_fma_f32 v[70:71], v[70:71], v[118:119], v[72:73]
	v_pk_fma_f32 v[72:73], v[66:67], v[114:115], v[74:75]
	v_pk_fma_f32 v[66:67], v[64:65], v[112:113], v[82:83]
	v_cvt_pk_bf16_f32 v64, v68, v69
	v_lshl_add_u64 v[68:69], v[78:79], 0, v[76:77]
	v_cvt_pk_bf16_f32 v65, v70, v71
	v_cvt_pk_bf16_f32 v66, v66, v67
	v_cvt_pk_bf16_f32 v67, v72, v73
	global_store_dwordx4 v[68:69], v[64:67], off offset:256

; __device__ __forceinline__ u32x4 pack8(f32x4 v0, f32x4 v1) { u32x4 w; w.x = cvt_pk_bf16(v0[0], v0[1]); w.y = cvt_pk_bf16(v0[2], v0[3]); w.z = cvt_pk_bf16(v1[0], v1[1]); w.w = cvt_pk_bf16(v1[2], v1[3]); return w; }
;     __device__ __forceinline__ void operator()(const f32x4 (&acc)[2][2][4][2], const Unit& u, int wr, int wc, int fr, int fq) const {
;     ...
;                         f32x4 b0, b1;
;                         if (xp) { const float* src = xp + (size_t)row * 2048 + col; b0 = *(const f32x4*)src; b1 = *(const f32x4*)(src + 4); }
;                         else { const u32x4 w = *(const u32x4*)(baseb + (size_t)row * 2048 + col);
;                             b0 = (f32x4){__builtin_bit_cast(float, w.x << 16), __builtin_bit_cast(float, w.x & 0xffff0000u), __builtin_bit_cast(float, w.y << 16), __builtin_bit_cast(float, w.y & 0xffff0000u)};
;                             b1 = (f32x4){__builtin_bit_cast(float, w.z << 16), __builtin_bit_cast(float, w.z & 0xffff0000u), __builtin_bit_cast(float, w.w << 16), __builtin_bit_cast(float, w.w & 0xffff0000u)}; }
;                         *(u32x4*)(outb + (size_t)row * 2048 + col) = pack8(b0 + g[bj][0] * acc[ai][bj][m][0], b1 + g[bj][1] * acc[ai][bj][m][1]); } } }
.LBB0_819:
	v_lshl_add_u64 v[84:85], s[14:15], 0, v[80:81]
	v_lshlrev_b64 v[88:89], 1, v[158:159]
	v_lshl_add_u64 v[84:85], v[84:85], 0, v[88:89]
	s_nop 0
	v_lshl_add_u64 v[90:91], s[62:63], 0, v[80:81]
	s_waitcnt vmcnt(7)
	v_lshlrev_b32_e32 v92, 16, v188
	v_and_b32_e32 v93, 0xffff0000, v188
	v_lshlrev_b32_e32 v84, 16, v189
	v_and_b32_e32 v85, 0xffff0000, v189
	v_lshlrev_b32_e32 v94, 16, v190
	v_and_b32_e32 v95, 0xffff0000, v190
	v_lshlrev_b32_e32 v86, 16, v191
	v_and_b32_e32 v87, 0xffff0000, v191
	v_pk_fma_f32 v[60:61], v[60:61], v[76:77], v[92:93]
	v_pk_fma_f32 v[62:63], v[62:63], v[78:79], v[84:85]
	v_pk_fma_f32 v[84:85], v[58:59], v[74:75], v[86:87]
	v_pk_fma_f32 v[58:59], v[56:57], v[72:73], v[94:95]
	v_cvt_pk_bf16_f32 v56, v60, v61
	v_lshl_add_u64 v[60:61], v[90:91], 0, v[88:89]
	v_cvt_pk_bf16_f32 v57, v62, v63
	v_cvt_pk_bf16_f32 v58, v58, v59
	v_cvt_pk_bf16_f32 v59, v84, v85
	global_store_dwordx4 v[60:61], v[56:59], off

; __device__ __forceinline__ u32x4 pack8(f32x4 v0, f32x4 v1) { u32x4 w; w.x = cvt_pk_bf16(v0[0], v0[1]); w.y = cvt_pk_bf16(v0[2], v0[3]); w.z = cvt_pk_bf16(v1[0], v1[1]); w.w = cvt_pk_bf16(v1[2], v1[3]); return w; }
;     __device__ __forceinline__ void operator()(const f32x4 (&acc)[2][2][4][2], const Unit& u, int wr, int wc, int fr, int fq) const {
;     ...
;                         f32x4 b0, b1;
;                         if (xp) { const float* src = xp + (size_t)row * 2048 + col; b0 = *(const f32x4*)src; b1 = *(const f32x4*)(src + 4); }
;                         else { const u32x4 w = *(const u32x4*)(baseb + (size_t)row * 2048 + col);
;                             b0 = (f32x4){__builtin_bit_cast(float, w.x << 16), __builtin_bit_cast(float, w.x & 0xffff0000u), __builtin_bit_cast(float, w.y << 16), __builtin_bit_cast(float, w.y & 0xffff0000u)};
;                             b1 = (f32x4){__builtin_bit_cast(float, w.z << 16), __builtin_bit_cast(float, w.z & 0xffff0000u), __builtin_bit_cast(float, w.w << 16), __builtin_bit_cast(float, w.w & 0xffff0000u)}; }
;                         *(u32x4*)(outb + (size_t)row * 2048 + col) = pack8(b0 + g[bj][0] * acc[ai][bj][m][0], b1 + g[bj][1] * acc[ai][bj][m][1]); } } }
.LBB0_822:
	s_nop 0
	v_lshl_add_u64 v[56:57], s[14:15], 0, v[80:81]
	v_lshlrev_b64 v[60:61], 1, v[158:159]
	v_lshl_add_u64 v[56:57], v[56:57], 0, v[60:61]
	s_nop 0
	v_lshl_add_u64 v[62:63], s[62:63], 0, v[80:81]
	s_waitcnt vmcnt(7)
	v_lshlrev_b32_e32 v80, 16, v192
	v_and_b32_e32 v81, 0xffff0000, v192
	v_lshlrev_b32_e32 v56, 16, v193
	v_and_b32_e32 v57, 0xffff0000, v193
	v_lshlrev_b32_e32 v82, 16, v194
	v_and_b32_e32 v83, 0xffff0000, v194
	v_lshlrev_b32_e32 v58, 16, v195
	v_and_b32_e32 v59, 0xffff0000, v195
	v_pk_fma_f32 v[52:53], v[52:53], v[68:69], v[80:81]
	v_pk_fma_f32 v[54:55], v[54:55], v[70:71], v[56:57]
	v_pk_fma_f32 v[56:57], v[50:51], v[66:67], v[58:59]
	v_pk_fma_f32 v[50:51], v[48:49], v[64:65], v[82:83]
	v_cvt_pk_bf16_f32 v48, v52, v53
	v_lshl_add_u64 v[52:53], v[62:63], 0, v[60:61]
	v_cvt_pk_bf16_f32 v49, v54, v55
	v_cvt_pk_bf16_f32 v50, v50, v51
	v_cvt_pk_bf16_f32 v51, v56, v57
	global_store_dwordx4 v[52:53], v[48:51], off offset:256

; __device__ __forceinline__ u32x4 pack8(f32x4 v0, f32x4 v1) { u32x4 w; w.x = cvt_pk_bf16(v0[0], v0[1]); w.y = cvt_pk_bf16(v0[2], v0[3]); w.z = cvt_pk_bf16(v1[0], v1[1]); w.w = cvt_pk_bf16(v1[2], v1[3]); return w; }
;     __device__ __forceinline__ void operator()(const f32x4 (&acc)[2][2][4][2], const Unit& u, int wr, int wc, int fr, int fq) const {
;     ...
;                         f32x4 b0, b1;
;                         if (xp) { const float* src = xp + (size_t)row * 2048 + col; b0 = *(const f32x4*)src; b1 = *(const f32x4*)(src + 4); }
;                         else { const u32x4 w = *(const u32x4*)(baseb + (size_t)row * 2048 + col);
;                             b0 = (f32x4){__builtin_bit_cast(float, w.x << 16), __builtin_bit_cast(float, w.x & 0xffff0000u), __builtin_bit_cast(float, w.y << 16), __builtin_bit_cast(float, w.y & 0xffff0000u)};
;                             b1 = (f32x4){__builtin_bit_cast(float, w.z << 16), __builtin_bit_cast(float, w.z & 0xffff0000u), __builtin_bit_cast(float, w.w << 16), __builtin_bit_cast(float, w.w & 0xffff0000u)}; }
;                         *(u32x4*)(outb + (size_t)row * 2048 + col) = pack8(b0 + g[bj][0] * acc[ai][bj][m][0], b1 + g[bj][1] * acc[ai][bj][m][1]); } } }
.LBB0_825:
	v_lshl_add_u64 v[52:53], s[14:15], 0, v[48:49]
	v_lshlrev_b64 v[56:57], 1, v[158:159]
	v_lshl_add_u64 v[52:53], v[52:53], 0, v[56:57]
	s_nop 0
	v_lshl_add_u64 v[58:59], s[62:63], 0, v[48:49]
	s_waitcnt vmcnt(7)
	v_lshlrev_b32_e32 v60, 16, v196
	v_and_b32_e32 v61, 0xffff0000, v196
	v_lshlrev_b32_e32 v52, 16, v197
	v_and_b32_e32 v53, 0xffff0000, v197
	v_lshlrev_b32_e32 v62, 16, v198
	v_and_b32_e32 v63, 0xffff0000, v198
	v_lshlrev_b32_e32 v54, 16, v199
	v_and_b32_e32 v55, 0xffff0000, v199
	v_pk_fma_f32 v[44:45], v[44:45], v[76:77], v[60:61]
	v_pk_fma_f32 v[46:47], v[46:47], v[78:79], v[52:53]
	v_pk_fma_f32 v[52:53], v[42:43], v[74:75], v[54:55]
	v_pk_fma_f32 v[42:43], v[40:41], v[72:73], v[62:63]
	v_cvt_pk_bf16_f32 v40, v44, v45
	v_lshl_add_u64 v[44:45], v[58:59], 0, v[56:57]
	v_cvt_pk_bf16_f32 v41, v46, v47
	v_cvt_pk_bf16_f32 v42, v42, v43
	v_cvt_pk_bf16_f32 v43, v52, v53
	global_store_dwordx4 v[44:45], v[40:43], off

; __device__ __forceinline__ u32x4 pack8(f32x4 v0, f32x4 v1) { u32x4 w; w.x = cvt_pk_bf16(v0[0], v0[1]); w.y = cvt_pk_bf16(v0[2], v0[3]); w.z = cvt_pk_bf16(v1[0], v1[1]); w.w = cvt_pk_bf16(v1[2], v1[3]); return w; }
;     __device__ __forceinline__ void operator()(const f32x4 (&acc)[2][2][4][2], const Unit& u, int wr, int wc, int fr, int fq) const {
;     ...
;                         f32x4 b0, b1;
;                         if (xp) { const float* src = xp + (size_t)row * 2048 + col; b0 = *(const f32x4*)src; b1 = *(const f32x4*)(src + 4); }
;                         else { const u32x4 w = *(const u32x4*)(baseb + (size_t)row * 2048 + col);
;                             b0 = (f32x4){__builtin_bit_cast(float, w.x << 16), __builtin_bit_cast(float, w.x & 0xffff0000u), __builtin_bit_cast(float, w.y << 16), __builtin_bit_cast(float, w.y & 0xffff0000u)};
;                             b1 = (f32x4){__builtin_bit_cast(float, w.z << 16), __builtin_bit_cast(float, w.z & 0xffff0000u), __builtin_bit_cast(float, w.w << 16), __builtin_bit_cast(float, w.w & 0xffff0000u)}; }
;                         *(u32x4*)(outb + (size_t)row * 2048 + col) = pack8(b0 + g[bj][0] * acc[ai][bj][m][0], b1 + g[bj][1] * acc[ai][bj][m][1]); } } }
.LBB0_828:
	s_nop 0
	v_lshl_add_u64 v[40:41], s[14:15], 0, v[48:49]
	v_lshlrev_b64 v[44:45], 1, v[158:159]
	v_lshl_add_u64 v[40:41], v[40:41], 0, v[44:45]
	s_nop 0
	v_lshl_add_u64 v[46:47], s[62:63], 0, v[48:49]
	s_waitcnt vmcnt(7)
	v_lshlrev_b32_e32 v48, 16, v200
	v_and_b32_e32 v49, 0xffff0000, v200
	v_lshlrev_b32_e32 v40, 16, v201
	v_and_b32_e32 v41, 0xffff0000, v201
	v_lshlrev_b32_e32 v50, 16, v202
	v_and_b32_e32 v51, 0xffff0000, v202
	v_lshlrev_b32_e32 v42, 16, v203
	v_and_b32_e32 v43, 0xffff0000, v203
	v_pk_fma_f32 v[36:37], v[36:37], v[68:69], v[48:49]
	v_pk_fma_f32 v[38:39], v[38:39], v[70:71], v[40:41]
	v_pk_fma_f32 v[40:41], v[34:35], v[66:67], v[42:43]
	v_pk_fma_f32 v[34:35], v[32:33], v[64:65], v[50:51]
	v_cvt_pk_bf16_f32 v32, v36, v37
	v_lshl_add_u64 v[36:37], v[46:47], 0, v[44:45]
	v_cvt_pk_bf16_f32 v33, v38, v39
	v_cvt_pk_bf16_f32 v34, v34, v35
	v_cvt_pk_bf16_f32 v35, v40, v41
	global_store_dwordx4 v[36:37], v[32:35], off offset:256

; __device__ __forceinline__ u32x4 pack8(f32x4 v0, f32x4 v1) { u32x4 w; w.x = cvt_pk_bf16(v0[0], v0[1]); w.y = cvt_pk_bf16(v0[2], v0[3]); w.z = cvt_pk_bf16(v1[0], v1[1]); w.w = cvt_pk_bf16(v1[2], v1[3]); return w; }
;     __device__ __forceinline__ void operator()(const f32x4 (&acc)[2][2][4][2], const Unit& u, int wr, int wc, int fr, int fq) const {
;     ...
;                         f32x4 b0, b1;
;                         if (xp) { const float* src = xp + (size_t)row * 2048 + col; b0 = *(const f32x4*)src; b1 = *(const f32x4*)(src + 4); }
;                         else { const u32x4 w = *(const u32x4*)(baseb + (size_t)row * 2048 + col);
;                             b0 = (f32x4){__builtin_bit_cast(float, w.x << 16), __builtin_bit_cast(float, w.x & 0xffff0000u), __builtin_bit_cast(float, w.y << 16), __builtin_bit_cast(float, w.y & 0xffff0000u)};
;                             b1 = (f32x4){__builtin_bit_cast(float, w.z << 16), __builtin_bit_cast(float, w.z & 0xffff0000u), __builtin_bit_cast(float, w.w << 16), __builtin_bit_cast(float, w.w & 0xffff0000u)}; }
;                         *(u32x4*)(outb + (size_t)row * 2048 + col) = pack8(b0 + g[bj][0] * acc[ai][bj][m][0], b1 + g[bj][1] * acc[ai][bj][m][1]); } } }
.LBB0_831:
	v_lshl_add_u64 v[36:37], s[14:15], 0, v[32:33]
	v_lshlrev_b64 v[40:41], 1, v[158:159]
	v_lshl_add_u64 v[36:37], v[36:37], 0, v[40:41]
	s_nop 0
	v_lshl_add_u64 v[42:43], s[62:63], 0, v[32:33]
	s_waitcnt vmcnt(7)
	v_lshlrev_b32_e32 v44, 16, v204
	v_and_b32_e32 v45, 0xffff0000, v204
	v_lshlrev_b32_e32 v36, 16, v205
	v_and_b32_e32 v37, 0xffff0000, v205
	v_lshlrev_b32_e32 v46, 16, v206
	v_and_b32_e32 v47, 0xffff0000, v206
	v_lshlrev_b32_e32 v38, 16, v207
	v_and_b32_e32 v39, 0xffff0000, v207
	v_pk_fma_f32 v[28:29], v[28:29], v[76:77], v[44:45]
	v_pk_fma_f32 v[30:31], v[30:31], v[78:79], v[36:37]
	v_pk_fma_f32 v[36:37], v[26:27], v[74:75], v[38:39]
	v_pk_fma_f32 v[26:27], v[24:25], v[72:73], v[46:47]
	v_cvt_pk_bf16_f32 v24, v28, v29
	v_lshl_add_u64 v[28:29], v[42:43], 0, v[40:41]
	v_cvt_pk_bf16_f32 v25, v30, v31
	v_cvt_pk_bf16_f32 v26, v26, v27
	v_cvt_pk_bf16_f32 v27, v36, v37
	global_store_dwordx4 v[28:29], v[24:27], off

; __device__ __forceinline__ u32x4 pack8(f32x4 v0, f32x4 v1) { u32x4 w; w.x = cvt_pk_bf16(v0[0], v0[1]); w.y = cvt_pk_bf16(v0[2], v0[3]); w.z = cvt_pk_bf16(v1[0], v1[1]); w.w = cvt_pk_bf16(v1[2], v1[3]); return w; }
;     __device__ __forceinline__ void operator()(const f32x4 (&acc)[2][2][4][2], const Unit& u, int wr, int wc, int fr, int fq) const {
;     ...
;                         f32x4 b0, b1;
;                         if (xp) { const float* src = xp + (size_t)row * 2048 + col; b0 = *(const f32x4*)src; b1 = *(const f32x4*)(src + 4); }
;                         else { const u32x4 w = *(const u32x4*)(baseb + (size_t)row * 2048 + col);
;                             b0 = (f32x4){__builtin_bit_cast(float, w.x << 16), __builtin_bit_cast(float, w.x & 0xffff0000u), __builtin_bit_cast(float, w.y << 16), __builtin_bit_cast(float, w.y & 0xffff0000u)};
;                             b1 = (f32x4){__builtin_bit_cast(float, w.z << 16), __builtin_bit_cast(float, w.z & 0xffff0000u), __builtin_bit_cast(float, w.w << 16), __builtin_bit_cast(float, w.w & 0xffff0000u)}; }
;                         *(u32x4*)(outb + (size_t)row * 2048 + col) = pack8(b0 + g[bj][0] * acc[ai][bj][m][0], b1 + g[bj][1] * acc[ai][bj][m][1]); } } }
.LBB0_834:
	s_nop 0
	v_lshl_add_u64 v[24:25], s[14:15], 0, v[32:33]
	v_lshlrev_b64 v[28:29], 1, v[158:159]
	v_lshl_add_u64 v[24:25], v[24:25], 0, v[28:29]
	s_nop 0
	v_lshl_add_u64 v[30:31], s[62:63], 0, v[32:33]
	s_waitcnt vmcnt(7)
	v_lshlrev_b32_e32 v32, 16, v208
	v_and_b32_e32 v33, 0xffff0000, v208
	v_lshlrev_b32_e32 v24, 16, v209
	v_and_b32_e32 v25, 0xffff0000, v209
	v_lshlrev_b32_e32 v34, 16, v210
	v_and_b32_e32 v35, 0xffff0000, v210
	v_lshlrev_b32_e32 v26, 16, v211
	v_and_b32_e32 v27, 0xffff0000, v211
	v_pk_fma_f32 v[20:21], v[20:21], v[68:69], v[32:33]
	v_pk_fma_f32 v[22:23], v[22:23], v[70:71], v[24:25]
	v_pk_fma_f32 v[24:25], v[18:19], v[66:67], v[26:27]
	v_pk_fma_f32 v[18:19], v[16:17], v[64:65], v[34:35]
	v_cvt_pk_bf16_f32 v16, v20, v21
	v_lshl_add_u64 v[20:21], v[30:31], 0, v[28:29]
	v_cvt_pk_bf16_f32 v17, v22, v23
	v_cvt_pk_bf16_f32 v18, v18, v19
	v_cvt_pk_bf16_f32 v19, v24, v25
	global_store_dwordx4 v[20:21], v[16:19], off offset:256

; __device__ __forceinline__ u32x4 pack8(f32x4 v0, f32x4 v1) { u32x4 w; w.x = cvt_pk_bf16(v0[0], v0[1]); w.y = cvt_pk_bf16(v0[2], v0[3]); w.z = cvt_pk_bf16(v1[0], v1[1]); w.w = cvt_pk_bf16(v1[2], v1[3]); return w; }
;     __device__ __forceinline__ void operator()(const f32x4 (&acc)[2][2][4][2], const Unit& u, int wr, int wc, int fr, int fq) const {
;     ...
;                         f32x4 b0, b1;
;                         if (xp) { const float* src = xp + (size_t)row * 2048 + col; b0 = *(const f32x4*)src; b1 = *(const f32x4*)(src + 4); }
;                         else { const u32x4 w = *(const u32x4*)(baseb + (size_t)row * 2048 + col);
;                             b0 = (f32x4){__builtin_bit_cast(float, w.x << 16), __builtin_bit_cast(float, w.x & 0xffff0000u), __builtin_bit_cast(float, w.y << 16), __builtin_bit_cast(float, w.y & 0xffff0000u)};
;                             b1 = (f32x4){__builtin_bit_cast(float, w.z << 16), __builtin_bit_cast(float, w.z & 0xffff0000u), __builtin_bit_cast(float, w.w << 16), __builtin_bit_cast(float, w.w & 0xffff0000u)}; }
;                         *(u32x4*)(outb + (size_t)row * 2048 + col) = pack8(b0 + g[bj][0] * acc[ai][bj][m][0], b1 + g[bj][1] * acc[ai][bj][m][1]); } } }
.LBB0_837:
	v_lshl_add_u64 v[20:21], s[14:15], 0, v[16:17]
	v_lshlrev_b64 v[24:25], 1, v[158:159]
	v_lshl_add_u64 v[20:21], v[20:21], 0, v[24:25]
	s_nop 0
	v_lshl_add_u64 v[26:27], s[62:63], 0, v[16:17]
	s_waitcnt vmcnt(7)
	v_lshlrev_b32_e32 v28, 16, v212
	v_and_b32_e32 v29, 0xffff0000, v212
	v_lshlrev_b32_e32 v20, 16, v213
	v_and_b32_e32 v21, 0xffff0000, v213
	v_lshlrev_b32_e32 v30, 16, v214
	v_and_b32_e32 v31, 0xffff0000, v214
	v_lshlrev_b32_e32 v22, 16, v215
	v_and_b32_e32 v23, 0xffff0000, v215
	v_pk_fma_f32 v[12:13], v[12:13], v[76:77], v[28:29]
	v_pk_fma_f32 v[14:15], v[14:15], v[78:79], v[20:21]
	v_pk_fma_f32 v[20:21], v[10:11], v[74:75], v[22:23]
	v_pk_fma_f32 v[10:11], v[8:9], v[72:73], v[30:31]
	v_cvt_pk_bf16_f32 v8, v12, v13
	v_lshl_add_u64 v[12:13], v[26:27], 0, v[24:25]
	v_cvt_pk_bf16_f32 v9, v14, v15
	v_cvt_pk_bf16_f32 v10, v10, v11
	v_cvt_pk_bf16_f32 v11, v20, v21
	global_store_dwordx4 v[12:13], v[8:11], off

; __device__ __forceinline__ u32x4 pack8(f32x4 v0, f32x4 v1) { u32x4 w; w.x = cvt_pk_bf16(v0[0], v0[1]); w.y = cvt_pk_bf16(v0[2], v0[3]); w.z = cvt_pk_bf16(v1[0], v1[1]); w.w = cvt_pk_bf16(v1[2], v1[3]); return w; }
;     __device__ __forceinline__ void operator()(const f32x4 (&acc)[2][2][4][2], const Unit& u, int wr, int wc, int fr, int fq) const {
;     ...
;                         f32x4 b0, b1;
;                         if (xp) { const float* src = xp + (size_t)row * 2048 + col; b0 = *(const f32x4*)src; b1 = *(const f32x4*)(src + 4); }
;                         else { const u32x4 w = *(const u32x4*)(baseb + (size_t)row * 2048 + col);
;                             b0 = (f32x4){__builtin_bit_cast(float, w.x << 16), __builtin_bit_cast(float, w.x & 0xffff0000u), __builtin_bit_cast(float, w.y << 16), __builtin_bit_cast(float, w.y & 0xffff0000u)};
;                             b1 = (f32x4){__builtin_bit_cast(float, w.z << 16), __builtin_bit_cast(float, w.z & 0xffff0000u), __builtin_bit_cast(float, w.w << 16), __builtin_bit_cast(float, w.w & 0xffff0000u)}; }
;                         *(u32x4*)(outb + (size_t)row * 2048 + col) = pack8(b0 + g[bj][0] * acc[ai][bj][m][0], b1 + g[bj][1] * acc[ai][bj][m][1]); } } }
.LBB0_840:
	s_nop 0
	v_lshl_add_u64 v[8:9], s[14:15], 0, v[16:17]
	v_lshlrev_b64 v[12:13], 1, v[158:159]
	v_lshl_add_u64 v[8:9], v[8:9], 0, v[12:13]
	s_nop 0
	v_lshl_add_u64 v[14:15], s[62:63], 0, v[16:17]
	s_waitcnt vmcnt(7)
	v_lshlrev_b32_e32 v16, 16, v216
	v_and_b32_e32 v17, 0xffff0000, v216
	v_lshlrev_b32_e32 v8, 16, v217
	v_and_b32_e32 v9, 0xffff0000, v217
	v_lshlrev_b32_e32 v18, 16, v218
	v_and_b32_e32 v19, 0xffff0000, v218
	v_lshlrev_b32_e32 v10, 16, v219
	v_and_b32_e32 v11, 0xffff0000, v219
	v_pk_fma_f32 v[4:5], v[4:5], v[68:69], v[16:17]
	v_pk_fma_f32 v[6:7], v[6:7], v[70:71], v[8:9]
	v_pk_fma_f32 v[8:9], v[2:3], v[66:67], v[10:11]
	v_pk_fma_f32 v[2:3], v[0:1], v[64:65], v[18:19]
	v_cvt_pk_bf16_f32 v0, v4, v5
	v_lshl_add_u64 v[4:5], v[14:15], 0, v[12:13]
	v_cvt_pk_bf16_f32 v1, v6, v7
	v_cvt_pk_bf16_f32 v2, v2, v3
	v_cvt_pk_bf16_f32 v3, v8, v9
	global_store_dwordx4 v[4:5], v[0:3], off offset:256

;     __device__ __forceinline__ void operator()(const f32x4 (&acc)[2][2][4][2], const Unit& u, int wr, int wc, int fr, int fq) const {
;     ...
;             for (int m = 0; m < 4; ++m) { const int row = row0 + ai * HALF + m * 16;
; #pragma unroll
;                 for (int bj = 0; bj < 2; ++bj) { const int col = col0 + bj * HALF;
;                     if (u.split) { float* pp = part + ((size_t)(u.k0 / u.nt) * (MROWS - MP) + (size_t)(row - MP)) * 2048 + col;
;                         *(f32x4*)pp = g[bj][0] * acc[ai][bj][m][0]; *(f32x4*)(pp + 4) = g[bj][1] * acc[ai][bj][m][1];
;                     } else {
;                         f32x4 b0, b1;
;                         if (xp) { const float* src = xp + (size_t)row * 2048 + col; b0 = *(const f32x4*)src; b1 = *(const f32x4*)(src + 4); }
;                         else { const u32x4 w = *(const u32x4*)(baseb + (size_t)row * 2048 + col);
.LBB0_845:
	v_lshlrev_b64 v[80:81], 12, v[160:161]
	v_lshl_add_u64 v[80:81], v[80:81], 0, s[38:39]
	v_lshl_add_u64 v[222:223], s[14:15], 0, v[80:81]
	v_lshlrev_b64 v[224:225], 1, v[158:159]
	v_lshl_add_u64 v[222:223], v[222:223], 0, v[224:225]
	global_load_dwordx4 v[188:191], v[222:223], off
	global_load_dwordx4 v[192:195], v[222:223], off offset:256
	v_add_co_u32_e32 v224, vcc, 0x10000, v222
	s_nop 1
	v_addc_co_u32_e32 v225, vcc, 0, v223, vcc
	global_load_dwordx4 v[196:199], v[224:225], off
	global_load_dwordx4 v[200:203], v[224:225], off offset:256
	v_add_co_u32_e32 v226, vcc, 0x20000, v222
	s_nop 1
	v_addc_co_u32_e32 v227, vcc, 0, v223, vcc
	global_load_dwordx4 v[204:207], v[226:227], off
	global_load_dwordx4 v[208:211], v[226:227], off offset:256
	v_add_co_u32_e32 v228, vcc, 0x30000, v222
	s_nop 1
	v_addc_co_u32_e32 v229, vcc, 0, v223, vcc
	global_load_dwordx4 v[212:215], v[228:229], off
	global_load_dwordx4 v[216:219], v[228:229], off offset:256
	s_branch .LBB0_819
